# static s_setprio 1 for waves 4-7 during the mixer (local/output) phases
# speedup vs baseline: 1.0063x; 1.0063x over previous
.LBB0_377:
	v_readfirstlane_b32 s98, v0
	s_nop 3
	s_lshr_b32 s98, s98, 6
	s_cmp_ge_u32 s98, 4
	s_cbranch_scc0 .Lprio_skip
	s_setprio 1

.LBB0_605:
	s_setprio 0
	v_readlane_b32 s84, v253, 43
	v_readlane_b32 s85, v253, 44
	v_readlane_b32 s86, v253, 45
	v_readlane_b32 s87, v253, 46
	v_readlane_b32 s96, v253, 47
	s_movk_i32 s97, 0x1ff
	s_mov_b32 s90, 0x1e000
	v_readlane_b32 s14, v253, 54
	v_readlane_b32 s15, v253, 55
